# prep_row rebalance: bias1 workgroups hand their 4th row to workgroups 64-127
# baseline (speedup 1.0000x reference)
; __global__ void __launch_bounds__(512, 2) fwd_megakernel(Args args) {
;     ...
;         for (int m = gw; m < M; m += NGW) prep_row(args.in[0] + (size_t)m * D, (bf16*)(ws + WS_H) + (size_t)m * D, (bf16*)(ws + WS_L) + (size_t)m * D, (float*)(ws + WS_SS) + (size_t)m * 8, lane);
.LBB0_199:
	s_or_b64 exec, exec, s[14:15]
	s_add_i32 s30, s30, s34
	v_lshl_add_u64 v[6:7], v[6:7], 0, s[8:9]
	v_lshl_add_u64 v[8:9], v[8:9], 0, s[10:11]
	s_cmpk_gt_i32 s30, 0x1fff
	v_lshl_add_u64 v[10:11], v[10:11], 0, s[12:13]
	s_cbranch_scc1 .Lprep_chk
	s_cmpk_lg_i32 s34, 0x800
	s_cbranch_scc1 .LBB0_200
	s_cmpk_lt_i32 s30, 0x1800
	s_cbranch_scc1 .LBB0_200
	s_cmpk_lt_i32 s30, 0x1a00
	s_cbranch_scc1 .LBB0_202
	s_branch .LBB0_200
.Lprep_chk:
	s_cmpk_lg_i32 s34, 0x800
	s_cbranch_scc1 .LBB0_202
	s_cmpk_lt_i32 s30, 0x2200
	s_cbranch_scc1 .LBB0_202
	s_cmpk_ge_i32 s30, 0x2400
	s_cbranch_scc1 .LBB0_202
	s_addk_i32 s30, 0xf600
	s_mov_b32 s15, -1
	s_mov_b32 s14, 0xfffec000
	v_lshl_add_u64 v[6:7], v[6:7], 0, s[14:15]
	s_mov_b32 s14, 0xff600000
	v_lshl_add_u64 v[8:9], v[8:9], 0, s[14:15]
	s_mov_b32 s14, 0xfec00000
	v_lshl_add_u64 v[10:11], v[10:11], 0, s[14:15]
